# v140 extended: redundant second accumulator zero-init removed in all 9 GEMM instances (incl. in_proj, FFN-up), first zero-init as 64 v_mov_b64
# baseline (speedup 1.0000x reference)
.LBB0_133:
	s_ashr_i32 s19, s18, 31
	s_lshl_b64 s[20:21], s[18:19], 20
	s_add_u32 s20, s30, s20
	s_addc_u32 s21, s31, s21
	s_ashr_i32 s17, s16, 31
	s_lshl_b64 s[22:23], s[16:17], 20
	v_readlane_b32 s28, v255, 37
	v_readlane_b32 s29, v255, 38
	s_add_u32 s22, s28, s22
	s_addc_u32 s23, s29, s23
	s_andn2_b64 vcc, exec, s[10:11]
	v_mov_b64_e32 v[2:3], 0
	v_mov_b64_e32 v[4:5], 0
	v_mov_b64_e32 v[6:7], 0
	v_mov_b64_e32 v[8:9], 0
	v_mov_b64_e32 v[10:11], 0
	v_mov_b64_e32 v[12:13], 0
	v_mov_b64_e32 v[14:15], 0
	v_mov_b64_e32 v[16:17], 0
	v_mov_b64_e32 v[18:19], 0
	v_mov_b64_e32 v[20:21], 0
	v_mov_b64_e32 v[22:23], 0
	v_mov_b64_e32 v[24:25], 0
	v_mov_b64_e32 v[26:27], 0
	v_mov_b64_e32 v[28:29], 0
	v_mov_b64_e32 v[30:31], 0
	v_mov_b64_e32 v[32:33], 0
	v_mov_b64_e32 v[34:35], 0
	v_mov_b64_e32 v[36:37], 0
	v_mov_b64_e32 v[38:39], 0
	v_mov_b64_e32 v[40:41], 0
	v_mov_b64_e32 v[42:43], 0
	v_mov_b64_e32 v[44:45], 0
	v_mov_b64_e32 v[46:47], 0
	v_mov_b64_e32 v[48:49], 0
	v_mov_b64_e32 v[50:51], 0
	v_mov_b64_e32 v[52:53], 0
	v_mov_b64_e32 v[54:55], 0
	v_mov_b64_e32 v[56:57], 0
	v_mov_b64_e32 v[58:59], 0
	v_mov_b64_e32 v[60:61], 0
	v_mov_b64_e32 v[62:63], 0
	v_mov_b64_e32 v[64:65], 0
	v_mov_b64_e32 v[66:67], 0
	v_mov_b64_e32 v[68:69], 0
	v_mov_b64_e32 v[70:71], 0
	v_mov_b64_e32 v[72:73], 0
	v_mov_b64_e32 v[74:75], 0
	v_mov_b64_e32 v[76:77], 0
	v_mov_b64_e32 v[78:79], 0
	v_mov_b64_e32 v[80:81], 0
	v_mov_b64_e32 v[82:83], 0
	v_mov_b64_e32 v[84:85], 0
	v_mov_b64_e32 v[86:87], 0
	v_mov_b64_e32 v[88:89], 0
	v_mov_b64_e32 v[90:91], 0
	v_mov_b64_e32 v[92:93], 0
	v_mov_b64_e32 v[94:95], 0
	v_mov_b64_e32 v[96:97], 0
	v_mov_b64_e32 v[98:99], 0
	v_mov_b64_e32 v[100:101], 0
	v_mov_b64_e32 v[102:103], 0
	v_mov_b64_e32 v[104:105], 0
	v_mov_b64_e32 v[106:107], 0
	v_mov_b64_e32 v[108:109], 0
	v_mov_b64_e32 v[110:111], 0
	v_mov_b64_e32 v[112:113], 0
	v_mov_b64_e32 v[114:115], 0
	v_mov_b64_e32 v[116:117], 0
	v_mov_b64_e32 v[118:119], 0
	v_mov_b64_e32 v[120:121], 0
	v_mov_b64_e32 v[122:123], 0
	v_mov_b64_e32 v[124:125], 0
	v_mov_b64_e32 v[126:127], 0
	v_mov_b64_e32 v[128:129], 0
	s_cbranch_vccnz .LBB0_137
	s_and_b64 s[28:29], s[4:5], exec
	s_cselect_b32 s17, s21, s25
	s_cselect_b32 s19, s20, s24
	s_cselect_b32 s49, s23, s27
	s_cselect_b32 s50, s22, s26
	s_add_u32 s24, s24, 0x80080
	s_addc_u32 s25, s25, 0
	s_add_u32 s56, s26, 0x100
	v_mov_b32_e32 v2, 0
	s_addc_u32 s57, s27, 0
	s_mov_b32 s26, 0

.LBB0_265:
	s_ashr_i32 s25, s24, 31
	s_lshl_b64 s[26:27], s[24:25], 19
	s_add_u32 s26, s60, s26
	s_addc_u32 s27, s61, s27
	s_ashr_i32 s23, s22, 31
	s_lshl_b64 s[28:29], s[22:23], 19
	s_add_u32 s28, s54, s28
	s_addc_u32 s29, s55, s29
	s_andn2_b64 vcc, exec, s[16:17]
	v_mov_b64_e32 v[2:3], 0
	v_mov_b64_e32 v[4:5], 0
	v_mov_b64_e32 v[6:7], 0
	v_mov_b64_e32 v[8:9], 0
	v_mov_b64_e32 v[10:11], 0
	v_mov_b64_e32 v[12:13], 0
	v_mov_b64_e32 v[14:15], 0
	v_mov_b64_e32 v[16:17], 0
	v_mov_b64_e32 v[18:19], 0
	v_mov_b64_e32 v[20:21], 0
	v_mov_b64_e32 v[22:23], 0
	v_mov_b64_e32 v[24:25], 0
	v_mov_b64_e32 v[26:27], 0
	v_mov_b64_e32 v[28:29], 0
	v_mov_b64_e32 v[30:31], 0
	v_mov_b64_e32 v[32:33], 0
	v_mov_b64_e32 v[34:35], 0
	v_mov_b64_e32 v[36:37], 0
	v_mov_b64_e32 v[38:39], 0
	v_mov_b64_e32 v[40:41], 0
	v_mov_b64_e32 v[42:43], 0
	v_mov_b64_e32 v[44:45], 0
	v_mov_b64_e32 v[46:47], 0
	v_mov_b64_e32 v[48:49], 0
	v_mov_b64_e32 v[50:51], 0
	v_mov_b64_e32 v[52:53], 0
	v_mov_b64_e32 v[54:55], 0
	v_mov_b64_e32 v[56:57], 0
	v_mov_b64_e32 v[58:59], 0
	v_mov_b64_e32 v[60:61], 0
	v_mov_b64_e32 v[62:63], 0
	v_mov_b64_e32 v[64:65], 0
	v_mov_b64_e32 v[66:67], 0
	v_mov_b64_e32 v[68:69], 0
	v_mov_b64_e32 v[70:71], 0
	v_mov_b64_e32 v[72:73], 0
	v_mov_b64_e32 v[74:75], 0
	v_mov_b64_e32 v[76:77], 0
	v_mov_b64_e32 v[78:79], 0
	v_mov_b64_e32 v[80:81], 0
	v_mov_b64_e32 v[82:83], 0
	v_mov_b64_e32 v[84:85], 0
	v_mov_b64_e32 v[86:87], 0
	v_mov_b64_e32 v[88:89], 0
	v_mov_b64_e32 v[90:91], 0
	v_mov_b64_e32 v[92:93], 0
	v_mov_b64_e32 v[94:95], 0
	v_mov_b64_e32 v[96:97], 0
	v_mov_b64_e32 v[98:99], 0
	v_mov_b64_e32 v[100:101], 0
	v_mov_b64_e32 v[102:103], 0
	v_mov_b64_e32 v[104:105], 0
	v_mov_b64_e32 v[106:107], 0
	v_mov_b64_e32 v[108:109], 0
	v_mov_b64_e32 v[110:111], 0
	v_mov_b64_e32 v[112:113], 0
	v_mov_b64_e32 v[114:115], 0
	v_mov_b64_e32 v[116:117], 0
	v_mov_b64_e32 v[118:119], 0
	v_mov_b64_e32 v[120:121], 0
	v_mov_b64_e32 v[122:123], 0
	v_mov_b64_e32 v[124:125], 0
	v_mov_b64_e32 v[126:127], 0
	v_mov_b64_e32 v[128:129], 0
	s_cbranch_vccnz .LBB0_268
	s_and_b64 s[36:37], s[4:5], exec
	s_cselect_b32 s3, s27, s31
	s_cselect_b32 s7, s26, s30
	s_cselect_b32 s9, s29, s35
	s_cselect_b32 s23, s28, s34
	s_add_u32 s30, s30, 0x40080
	s_addc_u32 s31, s31, 0
	s_add_u32 s25, s34, 0x100
	v_mov_b32_e32 v2, 0
	s_addc_u32 s48, s35, 0
	s_mov_b32 s34, 0

.LBB0_345:
	s_ashr_i32 s25, s24, 31
	s_lshl_b64 s[26:27], s[24:25], 20
	s_add_u32 s26, s38, s26
	s_addc_u32 s27, s39, s27
	s_ashr_i32 s23, s22, 31
	s_lshl_b64 s[28:29], s[22:23], 20
	v_readlane_b32 s36, v255, 51
	v_readlane_b32 s37, v255, 52
	s_add_u32 s28, s36, s28
	s_addc_u32 s29, s37, s29
	s_andn2_b64 vcc, exec, s[16:17]
	v_mov_b64_e32 v[2:3], 0
	v_mov_b64_e32 v[4:5], 0
	v_mov_b64_e32 v[6:7], 0
	v_mov_b64_e32 v[8:9], 0
	v_mov_b64_e32 v[10:11], 0
	v_mov_b64_e32 v[12:13], 0
	v_mov_b64_e32 v[14:15], 0
	v_mov_b64_e32 v[16:17], 0
	v_mov_b64_e32 v[18:19], 0
	v_mov_b64_e32 v[20:21], 0
	v_mov_b64_e32 v[22:23], 0
	v_mov_b64_e32 v[24:25], 0
	v_mov_b64_e32 v[26:27], 0
	v_mov_b64_e32 v[28:29], 0
	v_mov_b64_e32 v[30:31], 0
	v_mov_b64_e32 v[32:33], 0
	v_mov_b64_e32 v[34:35], 0
	v_mov_b64_e32 v[36:37], 0
	v_mov_b64_e32 v[38:39], 0
	v_mov_b64_e32 v[40:41], 0
	v_mov_b64_e32 v[42:43], 0
	v_mov_b64_e32 v[44:45], 0
	v_mov_b64_e32 v[46:47], 0
	v_mov_b64_e32 v[48:49], 0
	v_mov_b64_e32 v[50:51], 0
	v_mov_b64_e32 v[52:53], 0
	v_mov_b64_e32 v[54:55], 0
	v_mov_b64_e32 v[56:57], 0
	v_mov_b64_e32 v[58:59], 0
	v_mov_b64_e32 v[60:61], 0
	v_mov_b64_e32 v[62:63], 0
	v_mov_b64_e32 v[64:65], 0
	v_mov_b64_e32 v[66:67], 0
	v_mov_b64_e32 v[68:69], 0
	v_mov_b64_e32 v[70:71], 0
	v_mov_b64_e32 v[72:73], 0
	v_mov_b64_e32 v[74:75], 0
	v_mov_b64_e32 v[76:77], 0
	v_mov_b64_e32 v[78:79], 0
	v_mov_b64_e32 v[80:81], 0
	v_mov_b64_e32 v[82:83], 0
	v_mov_b64_e32 v[84:85], 0
	v_mov_b64_e32 v[86:87], 0
	v_mov_b64_e32 v[88:89], 0
	v_mov_b64_e32 v[90:91], 0
	v_mov_b64_e32 v[92:93], 0
	v_mov_b64_e32 v[94:95], 0
	v_mov_b64_e32 v[96:97], 0
	v_mov_b64_e32 v[98:99], 0
	v_mov_b64_e32 v[100:101], 0
	v_mov_b64_e32 v[102:103], 0
	v_mov_b64_e32 v[104:105], 0
	v_mov_b64_e32 v[106:107], 0
	v_mov_b64_e32 v[108:109], 0
	v_mov_b64_e32 v[110:111], 0
	v_mov_b64_e32 v[112:113], 0
	v_mov_b64_e32 v[114:115], 0
	v_mov_b64_e32 v[116:117], 0
	v_mov_b64_e32 v[118:119], 0
	v_mov_b64_e32 v[120:121], 0
	v_mov_b64_e32 v[122:123], 0
	v_mov_b64_e32 v[124:125], 0
	v_mov_b64_e32 v[126:127], 0
	v_mov_b64_e32 v[128:129], 0
	s_cbranch_vccnz .LBB0_349
	s_and_b64 s[36:37], s[4:5], exec
	s_cselect_b32 s23, s27, s31
	s_cselect_b32 s25, s26, s30
	s_cselect_b32 s70, s29, s35
	s_cselect_b32 s71, s28, s34
	s_add_u32 s30, s30, 0x80080
	s_addc_u32 s31, s31, 0
	s_add_u32 s74, s34, 0x100
	v_mov_b32_e32 v2, 0
	s_addc_u32 s75, s35, 0
	s_mov_b32 s34, 0

.LBB0_501:
	s_ashr_i32 s23, s22, 31
	s_lshl_b64 s[8:9], s[22:23], 19
	s_add_u32 s26, s60, s8
	s_addc_u32 s27, s61, s9
	s_ashr_i32 s21, s20, 31
	s_lshl_b64 s[8:9], s[20:21], 19
	v_readlane_b32 s28, v255, 43
	v_readlane_b32 s29, v255, 44
	s_add_u32 s28, s28, s8
	s_addc_u32 s29, s29, s9
	s_andn2_b64 vcc, exec, s[16:17]
	v_mov_b64_e32 v[2:3], 0
	v_mov_b64_e32 v[4:5], 0
	v_mov_b64_e32 v[6:7], 0
	v_mov_b64_e32 v[8:9], 0
	v_mov_b64_e32 v[10:11], 0
	v_mov_b64_e32 v[12:13], 0
	v_mov_b64_e32 v[14:15], 0
	v_mov_b64_e32 v[16:17], 0
	v_mov_b64_e32 v[18:19], 0
	v_mov_b64_e32 v[20:21], 0
	v_mov_b64_e32 v[22:23], 0
	v_mov_b64_e32 v[24:25], 0
	v_mov_b64_e32 v[26:27], 0
	v_mov_b64_e32 v[28:29], 0
	v_mov_b64_e32 v[30:31], 0
	v_mov_b64_e32 v[32:33], 0
	v_mov_b64_e32 v[34:35], 0
	v_mov_b64_e32 v[36:37], 0
	v_mov_b64_e32 v[38:39], 0
	v_mov_b64_e32 v[40:41], 0
	v_mov_b64_e32 v[42:43], 0
	v_mov_b64_e32 v[44:45], 0
	v_mov_b64_e32 v[46:47], 0
	v_mov_b64_e32 v[48:49], 0
	v_mov_b64_e32 v[50:51], 0
	v_mov_b64_e32 v[52:53], 0
	v_mov_b64_e32 v[54:55], 0
	v_mov_b64_e32 v[56:57], 0
	v_mov_b64_e32 v[58:59], 0
	v_mov_b64_e32 v[60:61], 0
	v_mov_b64_e32 v[62:63], 0
	v_mov_b64_e32 v[64:65], 0
	v_mov_b64_e32 v[66:67], 0
	v_mov_b64_e32 v[68:69], 0
	v_mov_b64_e32 v[70:71], 0
	v_mov_b64_e32 v[72:73], 0
	v_mov_b64_e32 v[74:75], 0
	v_mov_b64_e32 v[76:77], 0
	v_mov_b64_e32 v[78:79], 0
	v_mov_b64_e32 v[80:81], 0
	v_mov_b64_e32 v[82:83], 0
	v_mov_b64_e32 v[84:85], 0
	v_mov_b64_e32 v[86:87], 0
	v_mov_b64_e32 v[88:89], 0
	v_mov_b64_e32 v[90:91], 0
	v_mov_b64_e32 v[92:93], 0
	v_mov_b64_e32 v[94:95], 0
	v_mov_b64_e32 v[96:97], 0
	v_mov_b64_e32 v[98:99], 0
	v_mov_b64_e32 v[100:101], 0
	v_mov_b64_e32 v[102:103], 0
	v_mov_b64_e32 v[104:105], 0
	v_mov_b64_e32 v[106:107], 0
	v_mov_b64_e32 v[108:109], 0
	v_mov_b64_e32 v[110:111], 0
	v_mov_b64_e32 v[112:113], 0
	v_mov_b64_e32 v[114:115], 0
	v_mov_b64_e32 v[116:117], 0
	v_mov_b64_e32 v[118:119], 0
	v_mov_b64_e32 v[120:121], 0
	v_mov_b64_e32 v[122:123], 0
	v_mov_b64_e32 v[124:125], 0
	v_mov_b64_e32 v[126:127], 0
	v_mov_b64_e32 v[128:129], 0
	s_cbranch_vccnz .LBB0_505
	s_and_b64 s[8:9], s[4:5], exec
	s_cselect_b32 s21, s27, s31
	s_cselect_b32 s23, s26, s30
	s_cselect_b32 s70, s29, s35
	s_cselect_b32 s71, s28, s34
	s_add_u32 s30, s30, 0x40080
	s_addc_u32 s31, s31, 0
	s_add_u32 s74, s34, 0x100
	v_mov_b32_e32 v2, 0
	s_addc_u32 s75, s35, 0
	s_mov_b32 s34, 0

.LBB0_575:
	s_ashr_i32 s21, s20, 31
	s_lshl_b64 s[22:23], s[20:21], 19
	s_add_u32 s22, s60, s22
	s_addc_u32 s23, s61, s23
	s_ashr_i32 s19, s18, 31
	s_lshl_b64 s[24:25], s[18:19], 19
	s_add_u32 s24, s34, s24
	s_addc_u32 s25, s35, s25
	s_andn2_b64 vcc, exec, s[12:13]
	v_mov_b64_e32 v[2:3], 0
	v_mov_b64_e32 v[4:5], 0
	v_mov_b64_e32 v[6:7], 0
	v_mov_b64_e32 v[8:9], 0
	v_mov_b64_e32 v[10:11], 0
	v_mov_b64_e32 v[12:13], 0
	v_mov_b64_e32 v[14:15], 0
	v_mov_b64_e32 v[16:17], 0
	v_mov_b64_e32 v[18:19], 0
	v_mov_b64_e32 v[20:21], 0
	v_mov_b64_e32 v[22:23], 0
	v_mov_b64_e32 v[24:25], 0
	v_mov_b64_e32 v[26:27], 0
	v_mov_b64_e32 v[28:29], 0
	v_mov_b64_e32 v[30:31], 0
	v_mov_b64_e32 v[32:33], 0
	v_mov_b64_e32 v[34:35], 0
	v_mov_b64_e32 v[36:37], 0
	v_mov_b64_e32 v[38:39], 0
	v_mov_b64_e32 v[40:41], 0
	v_mov_b64_e32 v[42:43], 0
	v_mov_b64_e32 v[44:45], 0
	v_mov_b64_e32 v[46:47], 0
	v_mov_b64_e32 v[48:49], 0
	v_mov_b64_e32 v[50:51], 0
	v_mov_b64_e32 v[52:53], 0
	v_mov_b64_e32 v[54:55], 0
	v_mov_b64_e32 v[56:57], 0
	v_mov_b64_e32 v[58:59], 0
	v_mov_b64_e32 v[60:61], 0
	v_mov_b64_e32 v[62:63], 0
	v_mov_b64_e32 v[64:65], 0
	v_mov_b64_e32 v[66:67], 0
	v_mov_b64_e32 v[68:69], 0
	v_mov_b64_e32 v[70:71], 0
	v_mov_b64_e32 v[72:73], 0
	v_mov_b64_e32 v[74:75], 0
	v_mov_b64_e32 v[76:77], 0
	v_mov_b64_e32 v[78:79], 0
	v_mov_b64_e32 v[80:81], 0
	v_mov_b64_e32 v[82:83], 0
	v_mov_b64_e32 v[84:85], 0
	v_mov_b64_e32 v[86:87], 0
	v_mov_b64_e32 v[88:89], 0
	v_mov_b64_e32 v[90:91], 0
	v_mov_b64_e32 v[92:93], 0
	v_mov_b64_e32 v[94:95], 0
	v_mov_b64_e32 v[96:97], 0
	v_mov_b64_e32 v[98:99], 0
	v_mov_b64_e32 v[100:101], 0
	v_mov_b64_e32 v[102:103], 0
	v_mov_b64_e32 v[104:105], 0
	v_mov_b64_e32 v[106:107], 0
	v_mov_b64_e32 v[108:109], 0
	v_mov_b64_e32 v[110:111], 0
	v_mov_b64_e32 v[112:113], 0
	v_mov_b64_e32 v[114:115], 0
	v_mov_b64_e32 v[116:117], 0
	v_mov_b64_e32 v[118:119], 0
	v_mov_b64_e32 v[120:121], 0
	v_mov_b64_e32 v[122:123], 0
	v_mov_b64_e32 v[124:125], 0
	v_mov_b64_e32 v[126:127], 0
	v_mov_b64_e32 v[128:129], 0
	s_cbranch_vccnz .LBB0_579
	s_and_b64 s[30:31], s[4:5], exec
	s_cselect_b32 s7, s23, s27
	s_cselect_b32 s9, s22, s26
	s_cselect_b32 s19, s25, s29
	s_cselect_b32 s21, s24, s28
	s_add_u32 s26, s26, 0x40080
	s_addc_u32 s27, s27, 0
	s_add_u32 s71, s28, 0x100
	v_mov_b32_e32 v2, 0
	s_addc_u32 s74, s29, 0
	s_mov_b32 s28, 0
